# final RMSNorm rows (last layer, fused behind the output projection) rewritten by hand the same way: weights resident, row loads together, next row prefetched, counted vmcnt
# speedup vs baseline: 1.0014x; 1.0014x over previous
; __device__ __forceinline__ void final_rows(const float* X, const float* fw, float* out, int row0, int nrows, int wave, int lane) {
;     for (int row = row0 + wave; row < row0 + nrows; row += 8) {
;         const float4* xr = (const float4*)(X + (size_t)row * DM) + lane; float4 v[8]; float ss = 0.f;
; #pragma unroll
;         for (int j = 0; j < 8; ++j) { v[j] = xr[64 * j]; ss += v[j].x * v[j].x + v[j].y * v[j].y + v[j].z * v[j].z + v[j].w * v[j].w; }
;         const float r = rsqrtf(wave_sum(ss) * (1.f / DM) + EPS);
;         float4* op = (float4*)(out + (size_t)row * DM) + lane;
; #pragma unroll
;         for (int j = 0; j < 8; ++j) { const float4 w4 = *(const float4*)(fw + 4 * (lane + 64 * j)); op[64 * j] = make_float4(v[j].x * r * w4.x, v[j].y * r * w4.y, v[j].z * r * w4.z, v[j].w * r * w4.w); } }
.LBB0_1289:
	s_or_b64 exec, exec, s[34:35]
	v_ashrrev_i32_e32 v71, 6, v0
	v_and_b32_e32 v70, 63, v0
	s_mov_b64 s[6:7], -1
	s_and_b64 vcc, exec, s[0:1]
	v_cmp_gt_i32_e64 s[0:1], 32, v71
	s_barrier
	s_cbranch_vccz .LBB0_1294
	s_and_saveexec_b64 s[34:35], s[0:1]
	v_readlane_b32 s6, v253, 25
	s_cbranch_execz .LBB0_1293
	v_cmp_lt_i32_e32 vcc, v178, v172
	v_readlane_b32 s40, v254, 16
	v_lshlrev_b32_e32 v164, 4, v70
	v_cndmask_b32_e32 v0, v171, v178, vcc
	v_cmp_lt_i32_e32 vcc, v177, v172
	v_lshlrev_b32_e32 v72, 2, v0
	v_readlane_b32 s42, v254, 18
	v_cndmask_b32_e32 v0, v171, v177, vcc
	v_cmp_lt_i32_e32 vcc, v176, v172
	v_lshlrev_b32_e32 v73, 2, v0
	v_readlane_b32 s43, v254, 19
	v_cndmask_b32_e32 v0, v171, v176, vcc
	v_lshlrev_b32_e32 v74, 2, v0
	v_xor_b32_e32 v0, 8, v171
	v_cmp_lt_i32_e32 vcc, v0, v172
	v_lshl_add_u64 v[36:37], s[42:43], 0, v[164:165]
	s_mov_b64 s[0:1], 0x1000
	v_cndmask_b32_e32 v0, v171, v0, vcc
	v_lshlrev_b32_e32 v75, 2, v0
	v_xor_b32_e32 v0, 16, v171
	v_cmp_lt_i32_e32 vcc, v0, v172
	v_lshl_add_u64 v[38:39], v[36:37], 0, s[0:1]
	s_mov_b64 s[0:1], 0x1400
	v_cndmask_b32_e32 v0, v171, v0, vcc
	v_lshl_add_u64 v[40:41], v[36:37], 0, s[0:1]
	s_mov_b64 s[0:1], 0x1800
	v_lshlrev_b32_e32 v76, 2, v0
	v_xor_b32_e32 v0, 32, v171
	v_lshl_add_u64 v[42:43], v[36:37], 0, s[0:1]
	s_mov_b64 s[0:1], 0x1c00
	v_cmp_lt_i32_e32 vcc, v0, v172
	v_lshl_add_u64 v[44:45], v[36:37], 0, s[0:1]
	v_readlane_b32 s0, v254, 33
	v_cndmask_b32_e32 v0, v171, v0, vcc
	v_lshlrev_b32_e32 v77, 2, v0
	v_add_u32_e32 v78, s0, v71
	v_readlane_b32 s0, v254, 32
	v_readlane_b32 s44, v254, 20
	v_readlane_b32 s45, v254, 21
	v_add_u32_e32 v0, s0, v71
	v_ashrrev_i32_e32 v1, 31, v0
	v_readlane_b32 s46, v254, 22
	v_readlane_b32 s47, v254, 23
	v_lshlrev_b64 v[0:1], 13, v[0:1]
	v_lshl_add_u64 v[48:49], s[44:45], 0, v[0:1]
	v_lshl_add_u64 v[46:47], s[46:47], 0, v[0:1]
	s_mov_b64 s[0:1], 0
	v_readlane_b32 s41, v254, 17
	global_load_dwordx4 v[182:185], v[36:37], off
	global_load_dwordx4 v[186:189], v[36:37], off offset:1024
	global_load_dwordx4 v[190:193], v[36:37], off offset:2048
	global_load_dwordx4 v[194:197], v[36:37], off offset:3072
	global_load_dwordx4 v[198:201], v[38:39], off
	global_load_dwordx4 v[202:205], v[40:41], off
	global_load_dwordx4 v[206:209], v[42:43], off
	global_load_dwordx4 v[210:213], v[44:45], off
	v_lshl_add_u64 v[80:81], v[46:47], 0, v[164:165]
	v_add_co_u32_e32 v84, vcc, s17, v80
	s_nop 1
	v_addc_co_u32_e32 v85, vcc, 0, v81, vcc
	v_add_co_u32_e32 v82, vcc, 0xa000000, v80
	s_nop 1
	v_addc_co_u32_e32 v83, vcc, 0, v81, vcc
	global_load_dwordx4 v[100:103], v[82:83], off
	global_load_dwordx4 v[104:107], v[82:83], off offset:1024
	global_load_dwordx4 v[108:111], v[82:83], off offset:2048
	global_load_dwordx4 v[112:115], v[82:83], off offset:3072
	global_load_dwordx4 v[116:119], v[84:85], off
	global_load_dwordx4 v[120:123], v[84:85], off offset:1024
	global_load_dwordx4 v[124:127], v[84:85], off offset:2048
	global_load_dwordx4 v[128:131], v[84:85], off offset:3072
	v_lshl_add_u64 v[86:87], v[48:49], 0, v[164:165]
	v_add_co_u32_e32 v88, vcc, s16, v86
	s_nop 1
	v_addc_co_u32_e32 v89, vcc, 0, v87, vcc
	v_lshl_add_u64 v[46:47], v[46:47], 0, s[18:19]
	v_lshl_add_u64 v[48:49], v[48:49], 0, s[18:19]
	v_lshl_add_u64 v[80:81], v[46:47], 0, v[164:165]
	v_add_co_u32_e32 v84, vcc, s17, v80
	s_nop 1
	v_addc_co_u32_e32 v85, vcc, 0, v81, vcc
	v_add_co_u32_e32 v82, vcc, 0xa000000, v80
	s_nop 1
	v_addc_co_u32_e32 v83, vcc, 0, v81, vcc
	global_load_dwordx4 v[132:135], v[82:83], off
	global_load_dwordx4 v[136:139], v[82:83], off offset:1024
	global_load_dwordx4 v[140:143], v[82:83], off offset:2048
	global_load_dwordx4 v[144:147], v[82:83], off offset:3072
	global_load_dwordx4 v[148:151], v[84:85], off
	global_load_dwordx4 v[152:155], v[84:85], off offset:1024
	global_load_dwordx4 v[156:159], v[84:85], off offset:2048
	global_load_dwordx4 v[160:163], v[84:85], off offset:3072
	s_waitcnt vmcnt(8)
	v_mul_f32_e32 v9, v100, v100
	v_mul_f32_e32 v10, v101, v101
	v_mul_f32_e32 v11, v102, v102
	v_mul_f32_e32 v12, v103, v103
	v_add_f32_e32 v9, v9, v10
	v_add_f32_e32 v9, v9, v11
	v_add_f32_e32 v9, v9, v12
	v_mul_f32_e32 v8, v104, v104
	v_mul_f32_e32 v10, v105, v105
	v_mul_f32_e32 v11, v106, v106
	v_mul_f32_e32 v12, v107, v107
	v_add_f32_e32 v8, v8, v10
	v_add_f32_e32 v8, v8, v11
	v_add_f32_e32 v8, v8, v12
	v_add_f32_e32 v9, v9, v8
	v_mul_f32_e32 v8, v108, v108
	v_mul_f32_e32 v10, v109, v109
	v_mul_f32_e32 v11, v110, v110
	v_mul_f32_e32 v12, v111, v111
	v_add_f32_e32 v8, v8, v10
	v_add_f32_e32 v8, v8, v11
	v_add_f32_e32 v8, v8, v12
	v_add_f32_e32 v9, v9, v8
	v_mul_f32_e32 v8, v112, v112
	v_mul_f32_e32 v10, v113, v113
	v_mul_f32_e32 v11, v114, v114
	v_mul_f32_e32 v12, v115, v115
	v_add_f32_e32 v8, v8, v10
	v_add_f32_e32 v8, v8, v11
	v_add_f32_e32 v8, v8, v12
	v_add_f32_e32 v9, v9, v8
	v_mul_f32_e32 v8, v117, v117
	v_fmac_f32_e32 v8, v116, v116
	v_fmac_f32_e32 v8, v118, v118
	v_fmac_f32_e32 v8, v119, v119
	v_add_f32_e32 v9, v9, v8
	v_mul_f32_e32 v8, v121, v121
	v_fmac_f32_e32 v8, v120, v120
	v_fmac_f32_e32 v8, v122, v122
	v_fmac_f32_e32 v8, v123, v123
	v_add_f32_e32 v9, v9, v8
	v_mul_f32_e32 v8, v125, v125
	v_fmac_f32_e32 v8, v124, v124
	v_fmac_f32_e32 v8, v126, v126
	v_fmac_f32_e32 v8, v127, v127
	v_add_f32_e32 v9, v9, v8
	v_mul_f32_e32 v8, v129, v129
	v_fmac_f32_e32 v8, v128, v128
	v_fmac_f32_e32 v8, v130, v130
	v_fmac_f32_e32 v8, v131, v131
	v_add_f32_e32 v9, v9, v8
	ds_bpermute_b32 v8, v72, v9
	s_waitcnt lgkmcnt(0)
	v_add_f32_e32 v9, v9, v8
	ds_bpermute_b32 v8, v73, v9
	s_waitcnt lgkmcnt(0)
	v_add_f32_e32 v9, v9, v8
	ds_bpermute_b32 v8, v74, v9
	s_waitcnt lgkmcnt(0)
; __device__ __forceinline__ void final_rows(const float* X, const float* fw, float* out, int row0, int nrows, int wave, int lane) {
;     for (int row = row0 + wave; row < row0 + nrows; row += 8) {
;         const float4* xr = (const float4*)(X + (size_t)row * DM) + lane; float4 v[8]; float ss = 0.f;
; #pragma unroll
;         for (int j = 0; j < 8; ++j) { v[j] = xr[64 * j]; ss += v[j].x * v[j].x + v[j].y * v[j].y + v[j].z * v[j].z + v[j].w * v[j].w; }
;         const float r = rsqrtf(wave_sum(ss) * (1.f / DM) + EPS);
;         float4* op = (float4*)(out + (size_t)row * DM) + lane;
; #pragma unroll
;         for (int j = 0; j < 8; ++j) { const float4 w4 = *(const float4*)(fw + 4 * (lane + 64 * j)); op[64 * j] = make_float4(v[j].x * r * w4.x, v[j].y * r * w4.y, v[j].z * r * w4.z, v[j].w * r * w4.w); } }
	v_add_f32_e32 v9, v9, v8
	ds_bpermute_b32 v8, v75, v9
	s_waitcnt lgkmcnt(0)
	v_add_f32_e32 v9, v9, v8
	ds_bpermute_b32 v8, v76, v9
	s_waitcnt lgkmcnt(0)
	v_add_f32_e32 v9, v9, v8
	ds_bpermute_b32 v8, v77, v9
	s_waitcnt lgkmcnt(0)
	v_add_f32_e32 v9, v9, v8
	v_fmamk_f32 v9, v9, 0x3a000000, v179
	v_cmp_gt_f32_e32 vcc, s91, v9
	v_mul_f32_e32 v8, 0x4b800000, v9
	s_nop 0
	v_cndmask_b32_e32 v9, v9, v8, vcc
	v_rsq_f32_e32 v9, v9
	s_nop 0
	v_mul_f32_e32 v8, 0x45800000, v9
	v_cndmask_b32_e32 v13, v9, v8, vcc
	v_mul_f32_e32 v0, v100, v13
	v_mul_f32_e32 v1, v101, v13
	v_mul_f32_e32 v2, v102, v13
	v_mul_f32_e32 v3, v103, v13
	v_mul_f32_e32 v0, v182, v0
	v_mul_f32_e32 v1, v183, v1
	v_mul_f32_e32 v2, v184, v2
	v_mul_f32_e32 v3, v185, v3
	global_store_dwordx4 v[86:87], v[0:3], off
	v_mul_f32_e32 v4, v104, v13
	v_mul_f32_e32 v5, v105, v13
	v_mul_f32_e32 v6, v106, v13
	v_mul_f32_e32 v7, v107, v13
	v_mul_f32_e32 v4, v186, v4
	v_mul_f32_e32 v5, v187, v5
	v_mul_f32_e32 v6, v188, v6
	v_mul_f32_e32 v7, v189, v7
	global_store_dwordx4 v[86:87], v[4:7], off offset:1024
	v_mul_f32_e32 v0, v108, v13
	v_mul_f32_e32 v1, v109, v13
	v_mul_f32_e32 v2, v110, v13
	v_mul_f32_e32 v3, v111, v13
	v_mul_f32_e32 v0, v190, v0
	v_mul_f32_e32 v1, v191, v1
	v_mul_f32_e32 v2, v192, v2
	v_mul_f32_e32 v3, v193, v3
	global_store_dwordx4 v[86:87], v[0:3], off offset:2048
	v_mul_f32_e32 v4, v112, v13
	v_mul_f32_e32 v5, v113, v13
	v_mul_f32_e32 v6, v114, v13
	v_mul_f32_e32 v7, v115, v13
	v_mul_f32_e32 v4, v194, v4
	v_mul_f32_e32 v5, v195, v5
	v_mul_f32_e32 v6, v196, v6
	v_mul_f32_e32 v7, v197, v7
	global_store_dwordx4 v[86:87], v[4:7], off offset:3072
	v_mul_f32_e32 v0, v116, v13
	v_mul_f32_e32 v1, v117, v13
	v_mul_f32_e32 v2, v118, v13
	v_mul_f32_e32 v3, v119, v13
	v_mul_f32_e32 v0, v198, v0
	v_mul_f32_e32 v1, v199, v1
	v_mul_f32_e32 v2, v200, v2
	v_mul_f32_e32 v3, v201, v3
	global_store_dwordx4 v[88:89], v[0:3], off
	v_mul_f32_e32 v4, v120, v13
	v_mul_f32_e32 v5, v121, v13
	v_mul_f32_e32 v6, v122, v13
	v_mul_f32_e32 v7, v123, v13
	v_mul_f32_e32 v4, v202, v4
	v_mul_f32_e32 v5, v203, v5
	v_mul_f32_e32 v6, v204, v6
	v_mul_f32_e32 v7, v205, v7
	global_store_dwordx4 v[88:89], v[4:7], off offset:1024
	v_mul_f32_e32 v0, v124, v13
	v_mul_f32_e32 v1, v125, v13
	v_mul_f32_e32 v2, v126, v13
	v_mul_f32_e32 v3, v127, v13
	v_mul_f32_e32 v0, v206, v0
	v_mul_f32_e32 v1, v207, v1
	v_mul_f32_e32 v2, v208, v2
	v_mul_f32_e32 v3, v209, v3
	global_store_dwordx4 v[88:89], v[0:3], off offset:2048
	v_mul_f32_e32 v4, v128, v13
	v_mul_f32_e32 v5, v129, v13
	v_mul_f32_e32 v6, v130, v13
	v_mul_f32_e32 v7, v131, v13
	v_mul_f32_e32 v4, v210, v4
	v_mul_f32_e32 v5, v211, v5
	v_mul_f32_e32 v6, v212, v6
	v_mul_f32_e32 v7, v213, v7
	global_store_dwordx4 v[88:89], v[4:7], off offset:3072
	v_lshl_add_u64 v[86:87], v[48:49], 0, v[164:165]
	v_add_co_u32_e32 v88, vcc, s16, v86
	s_nop 1
	v_addc_co_u32_e32 v89, vcc, 0, v87, vcc
	v_lshl_add_u64 v[46:47], v[46:47], 0, s[18:19]
	v_lshl_add_u64 v[48:49], v[48:49], 0, s[18:19]
	v_lshl_add_u64 v[80:81], v[46:47], 0, v[164:165]
	v_add_co_u32_e32 v84, vcc, s17, v80
	s_nop 1
	v_addc_co_u32_e32 v85, vcc, 0, v81, vcc
	v_add_co_u32_e32 v82, vcc, 0xa000000, v80
	s_nop 1
	v_addc_co_u32_e32 v83, vcc, 0, v81, vcc
	global_load_dwordx4 v[100:103], v[82:83], off
	global_load_dwordx4 v[104:107], v[82:83], off offset:1024
	global_load_dwordx4 v[108:111], v[82:83], off offset:2048
	global_load_dwordx4 v[112:115], v[82:83], off offset:3072
	global_load_dwordx4 v[116:119], v[84:85], off
	global_load_dwordx4 v[120:123], v[84:85], off offset:1024
	global_load_dwordx4 v[124:127], v[84:85], off offset:2048
	global_load_dwordx4 v[128:131], v[84:85], off offset:3072
	s_waitcnt vmcnt(16)
	v_mul_f32_e32 v9, v132, v132
	v_mul_f32_e32 v10, v133, v133
	v_mul_f32_e32 v11, v134, v134
	v_mul_f32_e32 v12, v135, v135
	v_add_f32_e32 v9, v9, v10
	v_add_f32_e32 v9, v9, v11
	v_add_f32_e32 v9, v9, v12
	v_mul_f32_e32 v8, v136, v136
	v_mul_f32_e32 v10, v137, v137
	v_mul_f32_e32 v11, v138, v138
	v_mul_f32_e32 v12, v139, v139
	v_add_f32_e32 v8, v8, v10
	v_add_f32_e32 v8, v8, v11
	v_add_f32_e32 v8, v8, v12
	v_add_f32_e32 v9, v9, v8
	v_mul_f32_e32 v8, v140, v140
	v_mul_f32_e32 v10, v141, v141
	v_mul_f32_e32 v11, v142, v142
	v_mul_f32_e32 v12, v143, v143
	v_add_f32_e32 v8, v8, v10
	v_add_f32_e32 v8, v8, v11
	v_add_f32_e32 v8, v8, v12
	v_add_f32_e32 v9, v9, v8
	v_mul_f32_e32 v8, v144, v144
	v_mul_f32_e32 v10, v145, v145
	v_mul_f32_e32 v11, v146, v146
	v_mul_f32_e32 v12, v147, v147
	v_add_f32_e32 v8, v8, v10
	v_add_f32_e32 v8, v8, v11
	v_add_f32_e32 v8, v8, v12
	v_add_f32_e32 v9, v9, v8
	v_mul_f32_e32 v8, v149, v149
	v_fmac_f32_e32 v8, v148, v148
	v_fmac_f32_e32 v8, v150, v150
	v_fmac_f32_e32 v8, v151, v151
	v_add_f32_e32 v9, v9, v8
	v_mul_f32_e32 v8, v153, v153
	v_fmac_f32_e32 v8, v152, v152
	v_fmac_f32_e32 v8, v154, v154
	v_fmac_f32_e32 v8, v155, v155
	v_add_f32_e32 v9, v9, v8
	v_mul_f32_e32 v8, v157, v157
	v_fmac_f32_e32 v8, v156, v156
	v_fmac_f32_e32 v8, v158, v158
	v_fmac_f32_e32 v8, v159, v159
	v_add_f32_e32 v9, v9, v8
	v_mul_f32_e32 v8, v161, v161
	v_fmac_f32_e32 v8, v160, v160
	v_fmac_f32_e32 v8, v162, v162
	v_fmac_f32_e32 v8, v163, v163
	v_add_f32_e32 v9, v9, v8
	ds_bpermute_b32 v8, v72, v9
	s_waitcnt lgkmcnt(0)
	v_add_f32_e32 v9, v9, v8
	ds_bpermute_b32 v8, v73, v9
	s_waitcnt lgkmcnt(0)
	v_add_f32_e32 v9, v9, v8
	ds_bpermute_b32 v8, v74, v9
	s_waitcnt lgkmcnt(0)
	v_add_f32_e32 v9, v9, v8
	ds_bpermute_b32 v8, v75, v9
	s_waitcnt lgkmcnt(0)
	v_add_f32_e32 v9, v9, v8
	ds_bpermute_b32 v8, v76, v9
	s_waitcnt lgkmcnt(0)
	v_add_f32_e32 v9, v9, v8
	ds_bpermute_b32 v8, v77, v9
	s_waitcnt lgkmcnt(0)
; __device__ __forceinline__ void final_rows(const float* X, const float* fw, float* out, int row0, int nrows, int wave, int lane) {
;     for (int row = row0 + wave; row < row0 + nrows; row += 8) {
;         const float4* xr = (const float4*)(X + (size_t)row * DM) + lane; float4 v[8]; float ss = 0.f;
; #pragma unroll
;         for (int j = 0; j < 8; ++j) { v[j] = xr[64 * j]; ss += v[j].x * v[j].x + v[j].y * v[j].y + v[j].z * v[j].z + v[j].w * v[j].w; }
;         const float r = rsqrtf(wave_sum(ss) * (1.f / DM) + EPS);
;         float4* op = (float4*)(out + (size_t)row * DM) + lane;
; #pragma unroll
;         for (int j = 0; j < 8; ++j) { const float4 w4 = *(const float4*)(fw + 4 * (lane + 64 * j)); op[64 * j] = make_float4(v[j].x * r * w4.x, v[j].y * r * w4.y, v[j].z * r * w4.z, v[j].w * r * w4.w); } }
	v_add_f32_e32 v9, v9, v8
	v_fmamk_f32 v9, v9, 0x3a000000, v179
	v_cmp_gt_f32_e32 vcc, s91, v9
	v_mul_f32_e32 v8, 0x4b800000, v9
	s_nop 0
	v_cndmask_b32_e32 v9, v9, v8, vcc
	v_rsq_f32_e32 v9, v9
	s_nop 0
	v_mul_f32_e32 v8, 0x45800000, v9
	v_cndmask_b32_e32 v13, v9, v8, vcc
	v_mul_f32_e32 v0, v132, v13
	v_mul_f32_e32 v1, v133, v13
	v_mul_f32_e32 v2, v134, v13
	v_mul_f32_e32 v3, v135, v13
	v_mul_f32_e32 v0, v182, v0
	v_mul_f32_e32 v1, v183, v1
	v_mul_f32_e32 v2, v184, v2
	v_mul_f32_e32 v3, v185, v3
	global_store_dwordx4 v[86:87], v[0:3], off
	v_mul_f32_e32 v4, v136, v13
	v_mul_f32_e32 v5, v137, v13
	v_mul_f32_e32 v6, v138, v13
	v_mul_f32_e32 v7, v139, v13
	v_mul_f32_e32 v4, v186, v4
	v_mul_f32_e32 v5, v187, v5
	v_mul_f32_e32 v6, v188, v6
	v_mul_f32_e32 v7, v189, v7
	global_store_dwordx4 v[86:87], v[4:7], off offset:1024
	v_mul_f32_e32 v0, v140, v13
	v_mul_f32_e32 v1, v141, v13
	v_mul_f32_e32 v2, v142, v13
	v_mul_f32_e32 v3, v143, v13
	v_mul_f32_e32 v0, v190, v0
	v_mul_f32_e32 v1, v191, v1
	v_mul_f32_e32 v2, v192, v2
	v_mul_f32_e32 v3, v193, v3
	global_store_dwordx4 v[86:87], v[0:3], off offset:2048
	v_mul_f32_e32 v4, v144, v13
	v_mul_f32_e32 v5, v145, v13
	v_mul_f32_e32 v6, v146, v13
	v_mul_f32_e32 v7, v147, v13
	v_mul_f32_e32 v4, v194, v4
	v_mul_f32_e32 v5, v195, v5
	v_mul_f32_e32 v6, v196, v6
	v_mul_f32_e32 v7, v197, v7
	global_store_dwordx4 v[86:87], v[4:7], off offset:3072
	v_mul_f32_e32 v0, v148, v13
	v_mul_f32_e32 v1, v149, v13
	v_mul_f32_e32 v2, v150, v13
	v_mul_f32_e32 v3, v151, v13
	v_mul_f32_e32 v0, v198, v0
	v_mul_f32_e32 v1, v199, v1
	v_mul_f32_e32 v2, v200, v2
	v_mul_f32_e32 v3, v201, v3
	global_store_dwordx4 v[88:89], v[0:3], off
	v_mul_f32_e32 v4, v152, v13
	v_mul_f32_e32 v5, v153, v13
	v_mul_f32_e32 v6, v154, v13
	v_mul_f32_e32 v7, v155, v13
	v_mul_f32_e32 v4, v202, v4
	v_mul_f32_e32 v5, v203, v5
	v_mul_f32_e32 v6, v204, v6
	v_mul_f32_e32 v7, v205, v7
	global_store_dwordx4 v[88:89], v[4:7], off offset:1024
	v_mul_f32_e32 v0, v156, v13
	v_mul_f32_e32 v1, v157, v13
	v_mul_f32_e32 v2, v158, v13
	v_mul_f32_e32 v3, v159, v13
	v_mul_f32_e32 v0, v206, v0
	v_mul_f32_e32 v1, v207, v1
	v_mul_f32_e32 v2, v208, v2
	v_mul_f32_e32 v3, v209, v3
	global_store_dwordx4 v[88:89], v[0:3], off offset:2048
	v_mul_f32_e32 v4, v160, v13
	v_mul_f32_e32 v5, v161, v13
	v_mul_f32_e32 v6, v162, v13
	v_mul_f32_e32 v7, v163, v13
	v_mul_f32_e32 v4, v210, v4
	v_mul_f32_e32 v5, v211, v5
	v_mul_f32_e32 v6, v212, v6
	v_mul_f32_e32 v7, v213, v7
	global_store_dwordx4 v[88:89], v[4:7], off offset:3072
	v_lshl_add_u64 v[86:87], v[48:49], 0, v[164:165]
	v_add_co_u32_e32 v88, vcc, s16, v86
	s_nop 1
	v_addc_co_u32_e32 v89, vcc, 0, v87, vcc
	v_lshl_add_u64 v[46:47], v[46:47], 0, s[18:19]
	v_lshl_add_u64 v[48:49], v[48:49], 0, s[18:19]
	v_lshl_add_u64 v[80:81], v[46:47], 0, v[164:165]
	v_add_co_u32_e32 v84, vcc, s17, v80
	s_nop 1
	v_addc_co_u32_e32 v85, vcc, 0, v81, vcc
	v_add_co_u32_e32 v82, vcc, 0xa000000, v80
	s_nop 1
	v_addc_co_u32_e32 v83, vcc, 0, v81, vcc
	global_load_dwordx4 v[132:135], v[82:83], off
	global_load_dwordx4 v[136:139], v[82:83], off offset:1024
	global_load_dwordx4 v[140:143], v[82:83], off offset:2048
	global_load_dwordx4 v[144:147], v[82:83], off offset:3072
	global_load_dwordx4 v[148:151], v[84:85], off
	global_load_dwordx4 v[152:155], v[84:85], off offset:1024
	global_load_dwordx4 v[156:159], v[84:85], off offset:2048
	global_load_dwordx4 v[160:163], v[84:85], off offset:3072
	s_waitcnt vmcnt(16)
	v_mul_f32_e32 v9, v100, v100
	v_mul_f32_e32 v10, v101, v101
	v_mul_f32_e32 v11, v102, v102
	v_mul_f32_e32 v12, v103, v103
	v_add_f32_e32 v9, v9, v10
	v_add_f32_e32 v9, v9, v11
	v_add_f32_e32 v9, v9, v12
	v_mul_f32_e32 v8, v104, v104
	v_mul_f32_e32 v10, v105, v105
	v_mul_f32_e32 v11, v106, v106
	v_mul_f32_e32 v12, v107, v107
	v_add_f32_e32 v8, v8, v10
	v_add_f32_e32 v8, v8, v11
	v_add_f32_e32 v8, v8, v12
	v_add_f32_e32 v9, v9, v8
	v_mul_f32_e32 v8, v108, v108
	v_mul_f32_e32 v10, v109, v109
	v_mul_f32_e32 v11, v110, v110
	v_mul_f32_e32 v12, v111, v111
	v_add_f32_e32 v8, v8, v10
	v_add_f32_e32 v8, v8, v11
	v_add_f32_e32 v8, v8, v12
	v_add_f32_e32 v9, v9, v8
	v_mul_f32_e32 v8, v112, v112
	v_mul_f32_e32 v10, v113, v113
	v_mul_f32_e32 v11, v114, v114
	v_mul_f32_e32 v12, v115, v115
	v_add_f32_e32 v8, v8, v10
	v_add_f32_e32 v8, v8, v11
	v_add_f32_e32 v8, v8, v12
	v_add_f32_e32 v9, v9, v8
	v_mul_f32_e32 v8, v117, v117
	v_fmac_f32_e32 v8, v116, v116
	v_fmac_f32_e32 v8, v118, v118
	v_fmac_f32_e32 v8, v119, v119
	v_add_f32_e32 v9, v9, v8
	v_mul_f32_e32 v8, v121, v121
	v_fmac_f32_e32 v8, v120, v120
	v_fmac_f32_e32 v8, v122, v122
	v_fmac_f32_e32 v8, v123, v123
	v_add_f32_e32 v9, v9, v8
	v_mul_f32_e32 v8, v125, v125
	v_fmac_f32_e32 v8, v124, v124
	v_fmac_f32_e32 v8, v126, v126
	v_fmac_f32_e32 v8, v127, v127
	v_add_f32_e32 v9, v9, v8
	v_mul_f32_e32 v8, v129, v129
	v_fmac_f32_e32 v8, v128, v128
	v_fmac_f32_e32 v8, v130, v130
	v_fmac_f32_e32 v8, v131, v131
	v_add_f32_e32 v9, v9, v8
	ds_bpermute_b32 v8, v72, v9
	s_waitcnt lgkmcnt(0)
	v_add_f32_e32 v9, v9, v8
	ds_bpermute_b32 v8, v73, v9
	s_waitcnt lgkmcnt(0)
	v_add_f32_e32 v9, v9, v8
	ds_bpermute_b32 v8, v74, v9
	s_waitcnt lgkmcnt(0)
	v_add_f32_e32 v9, v9, v8
	ds_bpermute_b32 v8, v75, v9
	s_waitcnt lgkmcnt(0)
	v_add_f32_e32 v9, v9, v8
	ds_bpermute_b32 v8, v76, v9
	s_waitcnt lgkmcnt(0)
	v_add_f32_e32 v9, v9, v8
	ds_bpermute_b32 v8, v77, v9
	s_waitcnt lgkmcnt(0)
; __device__ __forceinline__ void final_rows(const float* X, const float* fw, float* out, int row0, int nrows, int wave, int lane) {
;     for (int row = row0 + wave; row < row0 + nrows; row += 8) {
;         const float4* xr = (const float4*)(X + (size_t)row * DM) + lane; float4 v[8]; float ss = 0.f;
; #pragma unroll
;         for (int j = 0; j < 8; ++j) { v[j] = xr[64 * j]; ss += v[j].x * v[j].x + v[j].y * v[j].y + v[j].z * v[j].z + v[j].w * v[j].w; }
;         const float r = rsqrtf(wave_sum(ss) * (1.f / DM) + EPS);
;         float4* op = (float4*)(out + (size_t)row * DM) + lane;
; #pragma unroll
;         for (int j = 0; j < 8; ++j) { const float4 w4 = *(const float4*)(fw + 4 * (lane + 64 * j)); op[64 * j] = make_float4(v[j].x * r * w4.x, v[j].y * r * w4.y, v[j].z * r * w4.z, v[j].w * r * w4.w); } }
	v_add_f32_e32 v9, v9, v8
	v_fmamk_f32 v9, v9, 0x3a000000, v179
	v_cmp_gt_f32_e32 vcc, s91, v9
	v_mul_f32_e32 v8, 0x4b800000, v9
	s_nop 0
	v_cndmask_b32_e32 v9, v9, v8, vcc
	v_rsq_f32_e32 v9, v9
	s_nop 0
	v_mul_f32_e32 v8, 0x45800000, v9
	v_cndmask_b32_e32 v13, v9, v8, vcc
	v_mul_f32_e32 v0, v100, v13
	v_mul_f32_e32 v1, v101, v13
	v_mul_f32_e32 v2, v102, v13
	v_mul_f32_e32 v3, v103, v13
	v_mul_f32_e32 v0, v182, v0
	v_mul_f32_e32 v1, v183, v1
	v_mul_f32_e32 v2, v184, v2
	v_mul_f32_e32 v3, v185, v3
	global_store_dwordx4 v[86:87], v[0:3], off
	v_mul_f32_e32 v4, v104, v13
	v_mul_f32_e32 v5, v105, v13
	v_mul_f32_e32 v6, v106, v13
	v_mul_f32_e32 v7, v107, v13
	v_mul_f32_e32 v4, v186, v4
	v_mul_f32_e32 v5, v187, v5
	v_mul_f32_e32 v6, v188, v6
	v_mul_f32_e32 v7, v189, v7
	global_store_dwordx4 v[86:87], v[4:7], off offset:1024
	v_mul_f32_e32 v0, v108, v13
	v_mul_f32_e32 v1, v109, v13
	v_mul_f32_e32 v2, v110, v13
	v_mul_f32_e32 v3, v111, v13
	v_mul_f32_e32 v0, v190, v0
	v_mul_f32_e32 v1, v191, v1
	v_mul_f32_e32 v2, v192, v2
	v_mul_f32_e32 v3, v193, v3
	global_store_dwordx4 v[86:87], v[0:3], off offset:2048
	v_mul_f32_e32 v4, v112, v13
	v_mul_f32_e32 v5, v113, v13
	v_mul_f32_e32 v6, v114, v13
	v_mul_f32_e32 v7, v115, v13
	v_mul_f32_e32 v4, v194, v4
	v_mul_f32_e32 v5, v195, v5
	v_mul_f32_e32 v6, v196, v6
	v_mul_f32_e32 v7, v197, v7
	global_store_dwordx4 v[86:87], v[4:7], off offset:3072
	v_mul_f32_e32 v0, v116, v13
	v_mul_f32_e32 v1, v117, v13
	v_mul_f32_e32 v2, v118, v13
	v_mul_f32_e32 v3, v119, v13
	v_mul_f32_e32 v0, v198, v0
	v_mul_f32_e32 v1, v199, v1
	v_mul_f32_e32 v2, v200, v2
	v_mul_f32_e32 v3, v201, v3
	global_store_dwordx4 v[88:89], v[0:3], off
	v_mul_f32_e32 v4, v120, v13
	v_mul_f32_e32 v5, v121, v13
	v_mul_f32_e32 v6, v122, v13
	v_mul_f32_e32 v7, v123, v13
	v_mul_f32_e32 v4, v202, v4
	v_mul_f32_e32 v5, v203, v5
	v_mul_f32_e32 v6, v204, v6
	v_mul_f32_e32 v7, v205, v7
	global_store_dwordx4 v[88:89], v[4:7], off offset:1024
	v_mul_f32_e32 v0, v124, v13
	v_mul_f32_e32 v1, v125, v13
	v_mul_f32_e32 v2, v126, v13
	v_mul_f32_e32 v3, v127, v13
	v_mul_f32_e32 v0, v206, v0
	v_mul_f32_e32 v1, v207, v1
	v_mul_f32_e32 v2, v208, v2
	v_mul_f32_e32 v3, v209, v3
	global_store_dwordx4 v[88:89], v[0:3], off offset:2048
	v_mul_f32_e32 v4, v128, v13
	v_mul_f32_e32 v5, v129, v13
	v_mul_f32_e32 v6, v130, v13
	v_mul_f32_e32 v7, v131, v13
	v_mul_f32_e32 v4, v210, v4
	v_mul_f32_e32 v5, v211, v5
	v_mul_f32_e32 v6, v212, v6
	v_mul_f32_e32 v7, v213, v7
	global_store_dwordx4 v[88:89], v[4:7], off offset:3072
	v_lshl_add_u64 v[86:87], v[48:49], 0, v[164:165]
	v_add_co_u32_e32 v88, vcc, s16, v86
	s_nop 1
	v_addc_co_u32_e32 v89, vcc, 0, v87, vcc
	s_waitcnt vmcnt(8)
	v_mul_f32_e32 v9, v132, v132
	v_mul_f32_e32 v10, v133, v133
	v_mul_f32_e32 v11, v134, v134
	v_mul_f32_e32 v12, v135, v135
	v_add_f32_e32 v9, v9, v10
	v_add_f32_e32 v9, v9, v11
	v_add_f32_e32 v9, v9, v12
	v_mul_f32_e32 v8, v136, v136
	v_mul_f32_e32 v10, v137, v137
	v_mul_f32_e32 v11, v138, v138
	v_mul_f32_e32 v12, v139, v139
	v_add_f32_e32 v8, v8, v10
	v_add_f32_e32 v8, v8, v11
	v_add_f32_e32 v8, v8, v12
	v_add_f32_e32 v9, v9, v8
	v_mul_f32_e32 v8, v140, v140
	v_mul_f32_e32 v10, v141, v141
	v_mul_f32_e32 v11, v142, v142
	v_mul_f32_e32 v12, v143, v143
	v_add_f32_e32 v8, v8, v10
	v_add_f32_e32 v8, v8, v11
	v_add_f32_e32 v8, v8, v12
	v_add_f32_e32 v9, v9, v8
	v_mul_f32_e32 v8, v144, v144
	v_mul_f32_e32 v10, v145, v145
	v_mul_f32_e32 v11, v146, v146
	v_mul_f32_e32 v12, v147, v147
	v_add_f32_e32 v8, v8, v10
	v_add_f32_e32 v8, v8, v11
	v_add_f32_e32 v8, v8, v12
	v_add_f32_e32 v9, v9, v8
	v_mul_f32_e32 v8, v149, v149
	v_fmac_f32_e32 v8, v148, v148
	v_fmac_f32_e32 v8, v150, v150
	v_fmac_f32_e32 v8, v151, v151
	v_add_f32_e32 v9, v9, v8
	v_mul_f32_e32 v8, v153, v153
	v_fmac_f32_e32 v8, v152, v152
	v_fmac_f32_e32 v8, v154, v154
	v_fmac_f32_e32 v8, v155, v155
	v_add_f32_e32 v9, v9, v8
	v_mul_f32_e32 v8, v157, v157
	v_fmac_f32_e32 v8, v156, v156
	v_fmac_f32_e32 v8, v158, v158
	v_fmac_f32_e32 v8, v159, v159
	v_add_f32_e32 v9, v9, v8
	v_mul_f32_e32 v8, v161, v161
	v_fmac_f32_e32 v8, v160, v160
	v_fmac_f32_e32 v8, v162, v162
	v_fmac_f32_e32 v8, v163, v163
	v_add_f32_e32 v9, v9, v8
	ds_bpermute_b32 v8, v72, v9
	s_waitcnt lgkmcnt(0)
; __device__ __forceinline__ void final_rows(const float* X, const float* fw, float* out, int row0, int nrows, int wave, int lane) {
;     for (int row = row0 + wave; row < row0 + nrows; row += 8) {
;         const float4* xr = (const float4*)(X + (size_t)row * DM) + lane; float4 v[8]; float ss = 0.f;
; #pragma unroll
;         for (int j = 0; j < 8; ++j) { v[j] = xr[64 * j]; ss += v[j].x * v[j].x + v[j].y * v[j].y + v[j].z * v[j].z + v[j].w * v[j].w; }
;         const float r = rsqrtf(wave_sum(ss) * (1.f / DM) + EPS);
;         float4* op = (float4*)(out + (size_t)row * DM) + lane;
; #pragma unroll
;         for (int j = 0; j < 8; ++j) { const float4 w4 = *(const float4*)(fw + 4 * (lane + 64 * j)); op[64 * j] = make_float4(v[j].x * r * w4.x, v[j].y * r * w4.y, v[j].z * r * w4.z, v[j].w * r * w4.w); } }
	v_add_f32_e32 v9, v9, v8
	ds_bpermute_b32 v8, v73, v9
	s_waitcnt lgkmcnt(0)
	v_add_f32_e32 v9, v9, v8
	ds_bpermute_b32 v8, v74, v9
	s_waitcnt lgkmcnt(0)
	v_add_f32_e32 v9, v9, v8
	ds_bpermute_b32 v8, v75, v9
	s_waitcnt lgkmcnt(0)
	v_add_f32_e32 v9, v9, v8
	ds_bpermute_b32 v8, v76, v9
	s_waitcnt lgkmcnt(0)
	v_add_f32_e32 v9, v9, v8
	ds_bpermute_b32 v8, v77, v9
	s_waitcnt lgkmcnt(0)
	v_add_f32_e32 v9, v9, v8
	v_fmamk_f32 v9, v9, 0x3a000000, v179
	v_cmp_gt_f32_e32 vcc, s91, v9
	v_mul_f32_e32 v8, 0x4b800000, v9
	s_nop 0
	v_cndmask_b32_e32 v9, v9, v8, vcc
	v_rsq_f32_e32 v9, v9
	s_nop 0
	v_mul_f32_e32 v8, 0x45800000, v9
	v_cndmask_b32_e32 v13, v9, v8, vcc
	v_mul_f32_e32 v0, v132, v13
	v_mul_f32_e32 v1, v133, v13
	v_mul_f32_e32 v2, v134, v13
	v_mul_f32_e32 v3, v135, v13
	v_mul_f32_e32 v0, v182, v0
	v_mul_f32_e32 v1, v183, v1
	v_mul_f32_e32 v2, v184, v2
	v_mul_f32_e32 v3, v185, v3
	global_store_dwordx4 v[86:87], v[0:3], off
	v_mul_f32_e32 v4, v136, v13
	v_mul_f32_e32 v5, v137, v13
	v_mul_f32_e32 v6, v138, v13
	v_mul_f32_e32 v7, v139, v13
	v_mul_f32_e32 v4, v186, v4
	v_mul_f32_e32 v5, v187, v5
	v_mul_f32_e32 v6, v188, v6
	v_mul_f32_e32 v7, v189, v7
	global_store_dwordx4 v[86:87], v[4:7], off offset:1024
	v_mul_f32_e32 v0, v140, v13
	v_mul_f32_e32 v1, v141, v13
	v_mul_f32_e32 v2, v142, v13
	v_mul_f32_e32 v3, v143, v13
	v_mul_f32_e32 v0, v190, v0
	v_mul_f32_e32 v1, v191, v1
	v_mul_f32_e32 v2, v192, v2
	v_mul_f32_e32 v3, v193, v3
	global_store_dwordx4 v[86:87], v[0:3], off offset:2048
	v_mul_f32_e32 v4, v144, v13
	v_mul_f32_e32 v5, v145, v13
	v_mul_f32_e32 v6, v146, v13
	v_mul_f32_e32 v7, v147, v13
	v_mul_f32_e32 v4, v194, v4
	v_mul_f32_e32 v5, v195, v5
	v_mul_f32_e32 v6, v196, v6
	v_mul_f32_e32 v7, v197, v7
	global_store_dwordx4 v[86:87], v[4:7], off offset:3072
	v_mul_f32_e32 v0, v148, v13
	v_mul_f32_e32 v1, v149, v13
	v_mul_f32_e32 v2, v150, v13
	v_mul_f32_e32 v3, v151, v13
	v_mul_f32_e32 v0, v198, v0
	v_mul_f32_e32 v1, v199, v1
	v_mul_f32_e32 v2, v200, v2
	v_mul_f32_e32 v3, v201, v3
	global_store_dwordx4 v[88:89], v[0:3], off
	v_mul_f32_e32 v4, v152, v13
	v_mul_f32_e32 v5, v153, v13
	v_mul_f32_e32 v6, v154, v13
	v_mul_f32_e32 v7, v155, v13
	v_mul_f32_e32 v4, v202, v4
	v_mul_f32_e32 v5, v203, v5
	v_mul_f32_e32 v6, v204, v6
	v_mul_f32_e32 v7, v205, v7
	global_store_dwordx4 v[88:89], v[4:7], off offset:1024
	v_mul_f32_e32 v0, v156, v13
	v_mul_f32_e32 v1, v157, v13
	v_mul_f32_e32 v2, v158, v13
	v_mul_f32_e32 v3, v159, v13
	v_mul_f32_e32 v0, v206, v0
	v_mul_f32_e32 v1, v207, v1
	v_mul_f32_e32 v2, v208, v2
	v_mul_f32_e32 v3, v209, v3
	global_store_dwordx4 v[88:89], v[0:3], off offset:2048
	v_mul_f32_e32 v4, v160, v13
	v_mul_f32_e32 v5, v161, v13
	v_mul_f32_e32 v6, v162, v13
	v_mul_f32_e32 v7, v163, v13
	v_mul_f32_e32 v4, v210, v4
	v_mul_f32_e32 v5, v211, v5
	v_mul_f32_e32 v6, v212, v6
	v_mul_f32_e32 v7, v213, v7
	global_store_dwordx4 v[88:89], v[4:7], off offset:3072
